# SSD chunk-output tile: previous-state fragment loads issued ~400 instructions (16 MFMAs) before their wait ladder instead of right in front of it
# speedup vs baseline: 1.0018x; 1.0018x over previous
.LBB0_1844:
	v_add_u32_e32 v10, s2, v1
	ds_read_b128 v[2:5], v10 offset:1024
	ds_read_b128 v[6:9], v10 offset:1536
	v_add_u32_e32 v11, 0x10800, v10
	s_add_i32 s2, s2, 64
	s_cmpk_eq_i32 s2, 0x100
	s_waitcnt lgkmcnt(0)
	v_mfma_f32_32x32x16_bf16 v[72:87], v[2:5], v[6:9], v[72:87]
	v_add_u32_e32 v6, 0x10a00, v10
	ds_read_b128 v[6:9], v6
	s_waitcnt lgkmcnt(0)
	v_mfma_f32_32x32x16_bf16 v[88:103], v[2:5], v[6:9], v[88:103]
	ds_read_b128 v[2:5], v11
	v_add_u32_e32 v11, 0x10820, v10
	s_waitcnt lgkmcnt(0)
	v_mfma_f32_32x32x16_bf16 v[48:63], v[2:5], v[6:9], v[48:63]
	ds_read_b128 v[2:5], v10 offset:1056
	ds_read_b128 v[6:9], v10 offset:1568
	s_waitcnt lgkmcnt(0)
	v_mfma_f32_32x32x16_bf16 v[72:87], v[2:5], v[6:9], v[72:87]
	v_add_u32_e32 v6, 0x10a20, v10
	ds_read_b128 v[6:9], v6
	s_waitcnt lgkmcnt(0)
	v_mfma_f32_32x32x16_bf16 v[88:103], v[2:5], v[6:9], v[88:103]
	ds_read_b128 v[2:5], v11
	s_waitcnt lgkmcnt(0)
	v_mfma_f32_32x32x16_bf16 v[48:63], v[2:5], v[6:9], v[48:63]
	s_cbranch_scc0 .LBB0_1844
	s_lshl_b32 s5, s56, 2
	s_ashr_i32 s53, s52, 31
	s_add_i32 s6, s5, 0
	s_lshl_b64 s[2:3], s[52:53], 17
	s_add_i32 s5, s6, 0x21000
	s_lshl_b64 s[16:17], s[58:59], 14
	s_add_u32 s2, s54, s2
	v_and_b32_e32 v1, 16, v134
	v_or_b32_e32 v185, 32, v186
	v_lshrrev_b32_e32 v2, 2, v134
	v_lshlrev_b32_e32 v188, 2, v186
	s_addc_u32 s3, s55, s3
	v_mov_b32_e32 v214, v112
	v_mov_b32_e32 v215, v137
	v_lshl_add_u64 v[214:215], s[2:3], 0, v[214:215]
	v_lshl_add_u64 v[214:215], s[16:17], 0, v[214:215]
	v_lshlrev_b32_e32 v224, 8, v186
	v_mov_b32_e32 v225, v137
	v_lshl_add_u64 v[214:215], v[214:215], 0, v[224:225]
	v_mov_b32_e32 v224, 0x1797e200
	v_lshl_add_u64 v[204:205], v[214:215], 0, v[224:225]
	v_mov_b32_e32 v224, 0x17980000
	v_lshl_add_u64 v[130:131], v[214:215], 0, v[224:225]
	global_load_dwordx4 v[216:219], v[204:205], off
	global_load_dwordx4 v[220:223], v[130:131], off offset:512
	global_load_dwordx4 v[144:147], v[204:205], off offset:32
	global_load_dwordx4 v[148:151], v[130:131], off offset:544
	global_load_dwordx4 v[152:155], v[204:205], off offset:64
	global_load_dwordx4 v[156:159], v[130:131], off offset:576
	global_load_dwordx4 v[160:163], v[204:205], off offset:96
	global_load_dwordx4 v[164:167], v[130:131], off offset:608
	global_load_dwordx4 v[168:171], v[204:205], off offset:128
	global_load_dwordx4 v[172:175], v[130:131], off offset:640
	global_load_dwordx4 v[176:179], v[204:205], off offset:160
	global_load_dwordx4 v[190:193], v[130:131], off offset:672
	global_load_dwordx4 v[194:197], v[204:205], off offset:192
	global_load_dwordx4 v[198:201], v[130:131], off offset:704
	global_load_dwordx4 v[202:205], v[204:205], off offset:224
	global_load_dwordx4 v[128:131], v[130:131], off offset:736
	v_lshlrev_b32_e32 v136, 3, v0
	v_add_u32_e32 v132, 0, v114
	v_add_u32_e32 v133, s6, v188
	v_add_u32_e32 v3, s5, v188
	ds_read2_b32 v[142:143], v3 offset1:32
	v_lshlrev_b32_e32 v187, 2, v0
	v_lshlrev_b32_e32 v0, 2, v134
	v_and_b32_e32 v0, 12, v0
	v_add_u32_e32 v113, s5, v112
	v_or3_b32 v0, v1, v0, s56
	v_and_or_b32 v16, v2, 3, v187
	v_lshlrev_b32_e32 v17, 1, v0
	ds_read_b128 v[0:3], v113
	ds_read_b128 v[4:7], v113 offset:32
	ds_read_b128 v[108:111], v113 offset:64
	ds_read_b128 v[104:107], v113 offset:96
	v_cmp_gt_u32_e32 vcc, v187, v186
	s_waitcnt lgkmcnt(3)
	v_sub_f32_e32 v8, v142, v0
	v_mul_f32_e32 v8, 0x3fb8aa3b, v8
	v_exp_f32_e32 v8, v8
	v_cmp_lt_u32_e64 s[44:45], v187, v186
	v_sub_f32_e32 v9, v142, v3
	v_mul_f32_e32 v9, 0x3fb8aa3b, v9
	v_mul_f32_e32 v8, v72, v8
	v_cndmask_b32_e64 v18, v8, 0, vcc
	v_sub_f32_e32 v8, v142, v1
	v_mul_f32_e32 v8, 0x3fb8aa3b, v8
	v_exp_f32_e32 v8, v8
	v_exp_f32_e32 v9, v9
	v_sub_f32_e32 v0, v143, v0
	v_sub_f32_e32 v1, v143, v1
	v_mul_f32_e32 v8, v73, v8
	v_cndmask_b32_e64 v19, 0, v8, s[44:45]
	v_sub_f32_e32 v8, v142, v2
	v_mul_f32_e32 v8, 0x3fb8aa3b, v8
	v_exp_f32_e32 v8, v8
	v_mul_f32_e32 v0, 0x3fb8aa3b, v0
	v_mul_f32_e32 v1, 0x3fb8aa3b, v1
	v_exp_f32_e32 v0, v0
	v_exp_f32_e32 v1, v1
	v_sub_f32_e32 v2, v143, v2
	v_sub_f32_e32 v3, v143, v3
	v_mul_f32_e32 v2, 0x3fb8aa3b, v2
	v_mul_f32_e32 v3, 0x3fb8aa3b, v3
	v_pk_mul_f32 v[10:11], v[74:75], v[8:9]
	s_waitcnt lgkmcnt(2)
	v_sub_f32_e32 v8, v142, v4
	v_sub_f32_e32 v9, v142, v5
	v_exp_f32_e32 v2, v2
	v_exp_f32_e32 v3, v3
	v_mul_f32_e32 v8, 0x3fb8aa3b, v8
	v_mul_f32_e32 v9, 0x3fb8aa3b, v9
	v_exp_f32_e32 v8, v8
	v_exp_f32_e32 v9, v9
	v_pk_mul_f32 v[0:1], v[88:89], v[0:1]
	s_waitcnt lgkmcnt(1)
	v_sub_f32_e32 v89, v142, v108
	v_mul_f32_e32 v89, 0x3fb8aa3b, v89
	v_pk_mul_f32 v[2:3], v[90:91], v[2:3]
	v_exp_f32_e32 v90, v89
	v_sub_f32_e32 v89, v142, v109
	v_mul_f32_e32 v89, 0x3fb8aa3b, v89
	v_pk_mul_f32 v[12:13], v[76:77], v[8:9]
	v_sub_f32_e32 v8, v142, v6
	v_sub_f32_e32 v9, v142, v7
	v_exp_f32_e32 v91, v89
	v_mul_f32_e32 v8, 0x3fb8aa3b, v8
	v_mul_f32_e32 v9, 0x3fb8aa3b, v9
	v_exp_f32_e32 v8, v8
	v_exp_f32_e32 v9, v9
	v_pk_mul_f32 v[80:81], v[80:81], v[90:91]
	v_sub_f32_e32 v90, v142, v110
	v_sub_f32_e32 v91, v142, v111
	v_or_b32_e32 v21, 2, v187
	v_mul_f32_e32 v90, 0x3fb8aa3b, v90
	v_mul_f32_e32 v91, 0x3fb8aa3b, v91
	v_or_b32_e32 v20, 3, v187
	v_pk_mul_f32 v[14:15], v[78:79], v[8:9]
	v_cvt_pk_bf16_f32 v9, v10, v11
	v_cmp_le_u32_e64 s[44:45], v21, v186
	v_exp_f32_e32 v90, v90
	v_exp_f32_e32 v91, v91
	v_cndmask_b32_e64 v10, 0, v9, s[44:45]
	v_lshrrev_b32_e32 v9, 16, v9
	v_cmp_le_u32_e64 s[44:45], v20, v186
	v_sub_f32_e32 v4, v143, v4
	v_sub_f32_e32 v5, v143, v5
	v_or_b32_e32 v23, 8, v187
	v_cndmask_b32_e64 v9, 0, v9, s[44:45]
	v_mul_f32_e32 v4, 0x3fb8aa3b, v4
	v_mul_f32_e32 v5, 0x3fb8aa3b, v5
	v_or_b32_e32 v22, 9, v187
	v_perm_b32 v9, v9, v10, s12
	v_cvt_pk_bf16_f32 v10, v12, v13
	v_cmp_le_u32_e64 s[44:45], v23, v186
	v_exp_f32_e32 v4, v4
	v_exp_f32_e32 v5, v5
	v_cndmask_b32_e64 v11, 0, v10, s[44:45]
	v_lshrrev_b32_e32 v10, 16, v10
	v_cmp_le_u32_e64 s[44:45], v22, v186
	v_sub_f32_e32 v6, v143, v6
	v_sub_f32_e32 v7, v143, v7
	v_pk_mul_f32 v[82:83], v[82:83], v[90:91]
	s_waitcnt lgkmcnt(0)
	v_sub_f32_e32 v90, v142, v104
	v_sub_f32_e32 v91, v142, v105
	v_or_b32_e32 v25, 10, v187
	v_cndmask_b32_e64 v10, 0, v10, s[44:45]
	v_mul_f32_e32 v6, 0x3fb8aa3b, v6
	v_mul_f32_e32 v7, 0x3fb8aa3b, v7
	v_mul_f32_e32 v90, 0x3fb8aa3b, v90
	v_mul_f32_e32 v91, 0x3fb8aa3b, v91
	v_or_b32_e32 v24, 11, v187
	v_perm_b32 v10, v10, v11, s12
	v_cvt_pk_bf16_f32 v11, v14, v15
	v_cmp_le_u32_e64 s[44:45], v25, v186
	v_exp_f32_e32 v6, v6
	v_exp_f32_e32 v7, v7
	v_exp_f32_e32 v90, v90
	v_exp_f32_e32 v91, v91
	v_cndmask_b32_e64 v12, 0, v11, s[44:45]
	v_lshrrev_b32_e32 v11, 16, v11
	v_cmp_le_u32_e64 s[44:45], v24, v186
	v_pk_mul_f32 v[4:5], v[92:93], v[4:5]
	v_or_b32_e32 v92, 16, v187
	v_cndmask_b32_e64 v11, 0, v11, s[44:45]
	v_or_b32_e32 v89, 17, v187
	v_cvt_pk_bf16_f32 v80, v80, v81
	v_cmp_le_u32_e64 s[44:45], v92, v186
	v_pk_mul_f32 v[6:7], v[94:95], v[6:7]
	v_or_b32_e32 v94, 18, v187
	v_cndmask_b32_e64 v81, 0, v80, s[44:45]
	v_lshrrev_b32_e32 v80, 16, v80
	v_cmp_le_u32_e64 s[44:45], v89, v186
	v_pk_mul_f32 v[84:85], v[84:85], v[90:91]
	v_sub_f32_e32 v90, v142, v106
	v_sub_f32_e32 v91, v142, v107
	v_cndmask_b32_e64 v80, 0, v80, s[44:45]
	v_or_b32_e32 v93, 19, v187
	v_mul_f32_e32 v90, 0x3fb8aa3b, v90
	v_mul_f32_e32 v91, 0x3fb8aa3b, v91
	v_perm_b32 v80, v80, v81, s12
	v_cvt_pk_bf16_f32 v81, v82, v83
	v_cmp_le_u32_e64 s[44:45], v94, v186
	v_exp_f32_e32 v90, v90
	v_exp_f32_e32 v91, v91
	v_cndmask_b32_e64 v82, 0, v81, s[44:45]
	v_lshrrev_b32_e32 v81, 16, v81
	v_cmp_le_u32_e64 s[44:45], v93, v186
	v_or_b32_e32 v115, 24, v187
	v_or_b32_e32 v95, 25, v187
	v_cndmask_b32_e64 v81, 0, v81, s[44:45]
	v_perm_b32 v81, v81, v82, s12
	v_cvt_pk_bf16_f32 v82, v84, v85
	v_cmp_le_u32_e64 s[44:45], v115, v186
	v_sub_f32_e32 v89, v143, v104
	v_mul_f32_e32 v89, 0x3fb8aa3b, v89
	v_cndmask_b32_e64 v83, 0, v82, s[44:45]
	v_lshrrev_b32_e32 v82, 16, v82
	v_cmp_le_u32_e64 s[44:45], v95, v186
	v_or_b32_e32 v117, 26, v187
	v_pk_mul_f32 v[86:87], v[86:87], v[90:91]
	v_cndmask_b32_e64 v82, 0, v82, s[44:45]
	v_exp_f32_e32 v90, v89
	v_sub_f32_e32 v89, v143, v105
	v_cvt_pk_bf16_f32 v0, v0, v1
	v_cvt_pk_bf16_f32 v1, v2, v3
	v_cvt_pk_bf16_f32 v2, v4, v5
	v_mul_u32_u24_e32 v4, 0x820, v16
	v_or_b32_e32 v116, 27, v187
	v_perm_b32 v82, v82, v83, s12
	v_cvt_pk_bf16_f32 v83, v86, v87
	v_cmp_le_u32_e64 s[44:45], v117, v186
	v_mul_f32_e32 v89, 0x3fb8aa3b, v89
	v_add3_u32 v88, 0, v17, v4
	v_cndmask_b32_e64 v84, 0, v83, s[44:45]
	v_lshrrev_b32_e32 v83, 16, v83
	v_cmp_le_u32_e64 s[44:45], v116, v186
	v_exp_f32_e32 v91, v89
	v_sub_f32_e32 v89, v143, v106
	v_cvt_pk_bf16_f32 v3, v6, v7
	ds_read_b64_tr_b16 v[4:5], v88
	ds_read_b64_tr_b16 v[6:7], v88 offset:16640
	v_cndmask_b32_e64 v83, 0, v83, s[44:45]
	v_mul_f32_e32 v89, 0x3fb8aa3b, v89
	v_perm_b32 v83, v83, v84, s12
	v_sub_f32_e32 v84, v143, v108
	v_sub_f32_e32 v85, v143, v109
	v_sub_f32_e32 v86, v143, v110
	v_sub_f32_e32 v87, v143, v111
	v_exp_f32_e32 v92, v89
	v_sub_f32_e32 v89, v143, v107
	v_mul_f32_e32 v84, 0x3fb8aa3b, v84
	v_mul_f32_e32 v85, 0x3fb8aa3b, v85
	v_mul_f32_e32 v86, 0x3fb8aa3b, v86
	v_mul_f32_e32 v87, 0x3fb8aa3b, v87
	v_mul_f32_e32 v89, 0x3fb8aa3b, v89
	v_exp_f32_e32 v84, v84
	v_exp_f32_e32 v85, v85
	v_exp_f32_e32 v86, v86
	v_exp_f32_e32 v87, v87
	v_exp_f32_e32 v93, v89
	v_cvt_pk_bf16_f32 v8, v18, v19
	v_perm_b32 v11, v11, v12, s12
	s_waitcnt lgkmcnt(0)
	v_mfma_f32_32x32x16_bf16 v[16:31], v[4:7], v[0:3], 0
	v_mul_f32_e64 v84, v96, v84
	v_mul_f32_e64 v85, v97, v85
	v_mul_f32_e64 v86, v98, v86
	v_mul_f32_e64 v87, v99, v87
	v_mul_f32_e64 v90, v100, v90
	v_mul_f32_e64 v91, v101, v91
	v_pk_mul_f32 v[92:93], v[102:103], v[92:93]
	v_cvt_pk_bf16_f32 v84, v84, v85
	v_cvt_pk_bf16_f32 v85, v86, v87
	v_cvt_pk_bf16_f32 v86, v90, v91
	v_mfma_f32_32x32x16_bf16 v[64:79], v[4:7], v[8:11], 0
	ds_read_b64_tr_b16 v[4:5], v88 offset:64
	ds_read_b64_tr_b16 v[6:7], v88 offset:16704
	v_cvt_pk_bf16_f32 v87, v92, v93
	ds_read_b64_tr_b16 v[90:91], v88 offset:33280
	ds_read_b64_tr_b16 v[92:93], v88 offset:49920
	v_or_b32_e32 v89, 33, v187
	s_add_u32 s2, s2, s16
	s_addc_u32 s3, s3, s17
	s_waitcnt lgkmcnt(2)
	v_mfma_f32_32x32x16_bf16 v[32:47], v[4:7], v[8:11], 0
	v_mfma_f32_32x32x16_bf16 v[0:15], v[4:7], v[0:3], 0
	s_waitcnt lgkmcnt(0)
	v_mfma_f32_32x32x16_bf16 v[64:79], v[90:93], v[80:83], v[64:79]
	v_mfma_f32_32x32x16_bf16 v[16:31], v[90:93], v[84:87], v[16:31]
	ds_read_b64_tr_b16 v[90:91], v88 offset:33344
	ds_read_b64_tr_b16 v[92:93], v88 offset:49984
	s_waitcnt lgkmcnt(0)
	v_mfma_f32_32x32x16_bf16 v[32:47], v[90:93], v[80:83], v[32:47]
	v_mfma_f32_32x32x16_bf16 v[0:15], v[90:93], v[84:87], v[0:15]
	ds_read_b128 v[90:93], v113 offset:128
	ds_read_b128 v[94:97], v113 offset:160
	ds_read_b128 v[84:87], v113 offset:192
	ds_read_b128 v[80:83], v113 offset:224
	s_waitcnt lgkmcnt(3)
	v_sub_f32_e32 v90, v143, v90
	v_mul_f32_e32 v90, 0x3fb8aa3b, v90
	v_exp_f32_e32 v90, v90
	s_nop 0
	v_mul_f32_e32 v48, v48, v90
	v_cndmask_b32_e64 v98, v48, 0, vcc
	v_sub_f32_e32 v48, v143, v91
	v_mul_f32_e32 v48, 0x3fb8aa3b, v48
	v_exp_f32_e32 v48, v48
	v_cmp_le_u32_e32 vcc, v89, v185
	v_mul_f32_e32 v48, v49, v48
	s_nop 0
	v_cndmask_b32_e32 v89, 0, v48, vcc
	v_sub_f32_e32 v48, v143, v92
	v_sub_f32_e32 v49, v143, v93
	v_mul_f32_e32 v48, 0x3fb8aa3b, v48
	v_mul_f32_e32 v49, 0x3fb8aa3b, v49
	v_exp_f32_e32 v48, v48
	v_exp_f32_e32 v49, v49
	v_or_b32_e32 v93, 34, v187
	v_or_b32_e32 v92, 35, v187
	v_cmp_le_u32_e32 vcc, v93, v185
	v_pk_mul_f32 v[48:49], v[50:51], v[48:49]
	s_waitcnt lgkmcnt(2)
	v_sub_f32_e32 v50, v143, v94
	v_sub_f32_e32 v51, v143, v95
	v_mul_f32_e32 v50, 0x3fb8aa3b, v50
	v_mul_f32_e32 v51, 0x3fb8aa3b, v51
	v_exp_f32_e32 v50, v50
	v_exp_f32_e32 v51, v51
	v_cvt_pk_bf16_f32 v48, v48, v49
	v_cndmask_b32_e32 v49, 0, v48, vcc
	v_lshrrev_b32_e32 v48, 16, v48
	v_pk_mul_f32 v[50:51], v[52:53], v[50:51]
	v_sub_f32_e32 v52, v143, v96
	v_sub_f32_e32 v53, v143, v97
	v_mul_f32_e32 v52, 0x3fb8aa3b, v52
	v_mul_f32_e32 v53, 0x3fb8aa3b, v53
	v_exp_f32_e32 v52, v52
	v_exp_f32_e32 v53, v53
	v_cmp_le_u32_e32 vcc, v92, v185
	v_or_b32_e32 v95, 40, v187
	v_or_b32_e32 v94, 41, v187
	v_cndmask_b32_e32 v48, 0, v48, vcc
	v_pk_mul_f32 v[90:91], v[54:55], v[52:53]
	v_perm_b32 v53, v48, v49, s12
	v_cvt_pk_bf16_f32 v48, v50, v51
	v_cmp_le_u32_e32 vcc, v95, v185
	v_or_b32_e32 v97, 42, v187
	v_or_b32_e32 v96, 43, v187
	v_cndmask_b32_e32 v49, 0, v48, vcc
	v_lshrrev_b32_e32 v48, 16, v48
	v_cmp_le_u32_e32 vcc, v94, v185
	v_cvt_pk_bf16_f32 v52, v98, v89
	v_add_u32_e32 v89, 0x10440, v88
	v_cndmask_b32_e32 v48, 0, v48, vcc
	v_perm_b32 v54, v48, v49, s12
	v_cvt_pk_bf16_f32 v48, v90, v91
	v_cmp_le_u32_e32 vcc, v97, v185
	s_nop 1
	v_cndmask_b32_e32 v49, 0, v48, vcc
	v_lshrrev_b32_e32 v48, 16, v48
	v_cmp_le_u32_e32 vcc, v96, v185
	s_nop 1
	v_cndmask_b32_e32 v48, 0, v48, vcc
	v_perm_b32 v55, v48, v49, s12
	v_add_u32_e32 v48, 0x10400, v88
	v_add_u32_e32 v49, 0x14500, v88
	ds_read_b64_tr_b16 v[90:91], v48
	ds_read_b64_tr_b16 v[92:93], v49
	v_mov_b64_e32 v[48:49], s[48:49]
	v_mov_b64_e32 v[50:51], s[50:51]
	s_waitcnt lgkmcnt(0)
	v_mfma_f32_32x32x16_bf16 v[16:31], v[90:93], v[52:55], v[16:31]
	v_mfma_f32_32x32x16_bf16 v[64:79], v[90:93], v[48:51], v[64:79]
	v_add_u32_e32 v92, 0x14540, v88
	ds_read_b64_tr_b16 v[90:91], v89
	ds_read_b64_tr_b16 v[92:93], v92
	s_waitcnt lgkmcnt(0)
	v_mfma_f32_32x32x16_bf16 v[0:15], v[90:93], v[52:55], v[0:15]
	v_sub_f32_e32 v52, v143, v84
	v_sub_f32_e32 v53, v143, v85
	v_mul_f32_e32 v52, 0x3fb8aa3b, v52
	v_mul_f32_e32 v53, 0x3fb8aa3b, v53
	v_exp_f32_e32 v52, v52
	v_exp_f32_e32 v53, v53
	v_sub_f32_e32 v54, v143, v86
	v_sub_f32_e32 v55, v143, v87
	v_mul_f32_e32 v54, 0x3fb8aa3b, v54
	v_mul_f32_e32 v55, 0x3fb8aa3b, v55
	v_exp_f32_e32 v54, v54
	v_exp_f32_e32 v55, v55
	v_or_b32_e32 v85, 48, v187
	v_pk_mul_f32 v[52:53], v[56:57], v[52:53]
	v_sub_f32_e32 v56, v143, v80
	v_sub_f32_e32 v57, v143, v81
	v_or_b32_e32 v84, 49, v187
	v_mul_f32_e32 v56, 0x3fb8aa3b, v56
	v_mul_f32_e32 v57, 0x3fb8aa3b, v57
	v_cvt_pk_bf16_f32 v52, v52, v53
	v_cmp_le_u32_e32 vcc, v85, v185
	v_exp_f32_e32 v56, v56
	v_exp_f32_e32 v57, v57
	v_cndmask_b32_e32 v53, 0, v52, vcc
	v_lshrrev_b32_e32 v52, 16, v52
	v_cmp_le_u32_e32 vcc, v84, v185
	v_or_b32_e32 v87, 50, v187
	v_pk_mul_f32 v[54:55], v[58:59], v[54:55]
	v_sub_f32_e32 v58, v143, v82
	v_sub_f32_e32 v59, v143, v83
	v_cndmask_b32_e32 v52, 0, v52, vcc
	v_or_b32_e32 v86, 51, v187
	v_mul_f32_e32 v58, 0x3fb8aa3b, v58
	v_mul_f32_e32 v59, 0x3fb8aa3b, v59
	v_perm_b32 v52, v52, v53, s12
	v_cvt_pk_bf16_f32 v53, v54, v55
	v_cmp_le_u32_e32 vcc, v87, v185
	v_exp_f32_e32 v58, v58
	v_exp_f32_e32 v59, v59
	v_cndmask_b32_e32 v54, 0, v53, vcc
	v_lshrrev_b32_e32 v53, 16, v53
	v_cmp_le_u32_e32 vcc, v86, v185
	v_or_b32_e32 v81, 56, v187
	v_pk_mul_f32 v[56:57], v[60:61], v[56:57]
	v_cndmask_b32_e32 v53, 0, v53, vcc
	v_or_b32_e32 v80, 57, v187
	v_perm_b32 v53, v53, v54, s12
	v_cvt_pk_bf16_f32 v54, v56, v57
	v_cmp_le_u32_e32 vcc, v81, v185
	v_or_b32_e32 v61, 58, v187
	v_pk_mul_f32 v[58:59], v[62:63], v[58:59]
	v_cndmask_b32_e32 v55, 0, v54, vcc
	v_lshrrev_b32_e32 v54, 16, v54
	v_cmp_le_u32_e32 vcc, v80, v185
	v_or_b32_e32 v60, 59, v187
	v_mfma_f32_32x32x16_bf16 v[32:47], v[90:93], v[48:51], v[32:47]
	v_cndmask_b32_e32 v54, 0, v54, vcc
	v_perm_b32 v54, v54, v55, s12
	v_cvt_pk_bf16_f32 v55, v58, v59
	v_cmp_le_u32_e32 vcc, v61, v185
	v_add_u32_e32 v58, 0x1c700, v88
	s_nop 0
	v_cndmask_b32_e32 v56, 0, v55, vcc
	v_lshrrev_b32_e32 v55, 16, v55
	v_cmp_le_u32_e32 vcc, v60, v185
	s_nop 1
	v_cndmask_b32_e32 v55, 0, v55, vcc
	v_perm_b32 v55, v55, v56, s12
	v_add_u32_e32 v56, 0x18600, v88
	ds_read_b64_tr_b16 v[56:57], v56
	ds_read_b64_tr_b16 v[58:59], v58
	s_waitcnt lgkmcnt(0)
	v_mfma_f32_32x32x16_bf16 v[64:79], v[56:59], v[48:51], v[64:79]
	v_mfma_f32_32x32x16_bf16 v[16:31], v[56:59], v[52:55], v[16:31]
	v_add_u32_e32 v56, 0x18640, v88
	v_add_u32_e32 v58, 0x1c740, v88
	ds_read_b64_tr_b16 v[56:57], v56
	ds_read_b64_tr_b16 v[58:59], v58
	s_waitcnt lgkmcnt(0)
	v_mfma_f32_32x32x16_bf16 v[32:47], v[56:59], v[48:51], v[32:47]
	v_mfma_f32_32x32x16_bf16 v[0:15], v[56:59], v[52:55], v[0:15]
	v_mov_b32_e32 v113, v137
	v_lshl_add_u64 v[48:49], s[2:3], 0, v[112:113]
	v_lshlrev_b32_e32 v50, 8, v186
	v_mov_b32_e32 v51, v137
	v_lshl_add_u64 v[52:53], v[48:49], 0, v[50:51]
	s_mov_b64 s[2:3], 0x1797e200
	v_lshl_add_u64 v[56:57], v[52:53], 0, s[2:3]
	s_mov_b32 s2, 0x1797e000
	v_add_co_u32_e32 v48, vcc, s2, v52
	s_mov_b32 s2, 0x17980000
	s_nop 0
	v_addc_co_u32_e32 v49, vcc, 0, v53, vcc
	v_add_co_u32_e32 v58, vcc, s2, v52
	s_nop 0
	v_addc_co_u32_e32 v59, vcc, 0, v53, vcc
	s_add_i32 s4, s4, 0
	v_add3_u32 v134, s4, v112, v114
	v_add_u32_e32 v135, 0x10400, v134
	s_waitcnt vmcnt(15)
	s_waitcnt vmcnt(14)
	s_waitcnt vmcnt(13)
	s_waitcnt vmcnt(12)
	s_waitcnt vmcnt(11)
	s_waitcnt vmcnt(10)
	s_waitcnt vmcnt(9)
	s_waitcnt vmcnt(8)
	s_waitcnt vmcnt(7)
	s_waitcnt vmcnt(6)
	s_waitcnt vmcnt(5)
	s_waitcnt vmcnt(4)
	s_waitcnt vmcnt(3)
	s_waitcnt vmcnt(2)
	s_waitcnt vmcnt(1)
	s_waitcnt vmcnt(0)
	ds_read_b128 v[56:59], v134 offset:1536
	ds_read_b128 v[206:209], v134 offset:1568
	ds_read_b128 v[60:63], v135 offset:1536
	ds_read_b128 v[210:213], v135 offset:1568
	s_waitcnt lgkmcnt(3)
	v_mfma_f32_32x32x16_bf16 v[112:127], v[216:219], v[56:59], 0
	s_waitcnt lgkmcnt(1)
	v_mfma_f32_32x32x16_bf16 v[80:95], v[216:219], v[60:63], 0
	v_mfma_f32_32x32x16_bf16 v[96:111], v[220:223], v[56:59], 0
	v_mfma_f32_32x32x16_bf16 v[48:63], v[220:223], v[60:63], 0
	v_mfma_f32_32x32x16_bf16 v[112:127], v[144:147], v[206:209], v[112:127]
	s_waitcnt lgkmcnt(0)
	v_mfma_f32_32x32x16_bf16 v[80:95], v[144:147], v[210:213], v[80:95]
	ds_read_b128 v[144:147], v134 offset:1600
	v_mfma_f32_32x32x16_bf16 v[96:111], v[148:151], v[206:209], v[96:111]
	v_mfma_f32_32x32x16_bf16 v[48:63], v[148:151], v[210:213], v[48:63]
	ds_read_b128 v[148:151], v135 offset:1600
	s_waitcnt lgkmcnt(1)
	v_mfma_f32_32x32x16_bf16 v[112:127], v[152:155], v[144:147], v[112:127]
	s_waitcnt lgkmcnt(0)
	v_mfma_f32_32x32x16_bf16 v[80:95], v[152:155], v[148:151], v[80:95]
	v_mfma_f32_32x32x16_bf16 v[96:111], v[156:159], v[144:147], v[96:111]
	ds_read_b128 v[144:147], v134 offset:1632
	v_mfma_f32_32x32x16_bf16 v[48:63], v[156:159], v[148:151], v[48:63]
	ds_read_b128 v[148:151], v135 offset:1632
	s_waitcnt lgkmcnt(1)
	v_mfma_f32_32x32x16_bf16 v[112:127], v[160:163], v[144:147], v[112:127]
	s_waitcnt lgkmcnt(0)
	v_mfma_f32_32x32x16_bf16 v[80:95], v[160:163], v[148:151], v[80:95]
	v_mfma_f32_32x32x16_bf16 v[96:111], v[164:167], v[144:147], v[96:111]
	ds_read_b128 v[144:147], v134 offset:1664
	v_mfma_f32_32x32x16_bf16 v[48:63], v[164:167], v[148:151], v[48:63]
	ds_read_b128 v[148:151], v135 offset:1664
	s_waitcnt lgkmcnt(1)
	v_mfma_f32_32x32x16_bf16 v[112:127], v[168:171], v[144:147], v[112:127]
	s_waitcnt lgkmcnt(0)
	v_mfma_f32_32x32x16_bf16 v[80:95], v[168:171], v[148:151], v[80:95]
	v_mfma_f32_32x32x16_bf16 v[96:111], v[172:175], v[144:147], v[96:111]
	ds_read_b128 v[144:147], v134 offset:1696
	v_mfma_f32_32x32x16_bf16 v[48:63], v[172:175], v[148:151], v[48:63]
	ds_read_b128 v[148:151], v135 offset:1696
	s_waitcnt lgkmcnt(1)
	v_mfma_f32_32x32x16_bf16 v[112:127], v[176:179], v[144:147], v[112:127]
	s_waitcnt lgkmcnt(0)
	v_mfma_f32_32x32x16_bf16 v[80:95], v[176:179], v[148:151], v[80:95]
	v_mfma_f32_32x32x16_bf16 v[96:111], v[190:193], v[144:147], v[96:111]
	ds_read_b128 v[144:147], v134 offset:1728
	v_mfma_f32_32x32x16_bf16 v[48:63], v[190:193], v[148:151], v[48:63]
	ds_read_b128 v[148:151], v135 offset:1728
	s_waitcnt lgkmcnt(1)
	v_mfma_f32_32x32x16_bf16 v[112:127], v[194:197], v[144:147], v[112:127]
	s_waitcnt lgkmcnt(0)
	v_mfma_f32_32x32x16_bf16 v[80:95], v[194:197], v[148:151], v[80:95]
	v_mfma_f32_32x32x16_bf16 v[96:111], v[198:201], v[144:147], v[96:111]
	ds_read_b128 v[144:147], v134 offset:1760
	v_mfma_f32_32x32x16_bf16 v[48:63], v[198:201], v[148:151], v[48:63]
	ds_read_b128 v[148:151], v135 offset:1760
	v_mul_f32_e32 v134, 0x3fb8aa3b, v142
	v_exp_f32_e32 v142, v134
	s_waitcnt lgkmcnt(1)
	v_mfma_f32_32x32x16_bf16 v[112:127], v[202:205], v[144:147], v[112:127]
	s_waitcnt lgkmcnt(0)
	v_mfma_f32_32x32x16_bf16 v[80:95], v[202:205], v[148:151], v[80:95]
	v_mfma_f32_32x32x16_bf16 v[96:111], v[128:131], v[144:147], v[96:111]
	v_mfma_f32_32x32x16_bf16 v[48:63], v[128:131], v[148:151], v[48:63]
	s_load_dwordx2 s[2:3], s[0:1], 0x70
	v_or_b32_e32 v144, s15, v186
	v_ashrrev_i32_e32 v145, 31, v144
	v_lshlrev_b64 v[130:131], 10, v[144:145]
	v_or_b32_e32 v140, s15, v185
	s_waitcnt lgkmcnt(0)
	s_add_u32 s2, s2, s36
	s_addc_u32 s3, s3, s37
	s_ashr_i32 s57, s56, 31
	s_lshl_b64 s[4:5], s[56:57], 1
	global_load_dword v189, v137, s[2:3]
	s_add_u32 s2, s54, s4
	s_addc_u32 s3, s55, s5
	v_lshl_add_u64 v[128:129], s[2:3], 0, v[136:137]
	s_mov_b64 s[2:3], 0xd6fe200
	v_lshl_add_u64 v[128:129], v[128:129], 0, s[2:3]
	v_lshl_add_u64 v[130:131], v[128:129], 0, v[130:131]
	v_ashrrev_i32_e32 v141, 31, v140
	global_load_dwordx2 v[178:179], v[130:131], off
	global_load_dwordx2 v[176:177], v[130:131], off offset:16
	global_load_dwordx2 v[174:175], v[130:131], off offset:32
	global_load_dwordx2 v[172:173], v[130:131], off offset:48
	global_load_dwordx2 v[170:171], v[130:131], off offset:64
	global_load_dwordx2 v[168:169], v[130:131], off offset:80
	global_load_dwordx2 v[166:167], v[130:131], off offset:96
	global_load_dwordx2 v[164:165], v[130:131], off offset:112
	v_lshlrev_b64 v[130:131], 10, v[140:141]
	v_lshl_add_u64 v[128:129], v[128:129], 0, v[130:131]
	global_load_dwordx2 v[160:161], v[128:129], off
	global_load_dwordx2 v[158:159], v[128:129], off offset:16
	global_load_dwordx2 v[156:157], v[128:129], off offset:32
	global_load_dwordx2 v[154:155], v[128:129], off offset:48
	global_load_dwordx2 v[152:153], v[128:129], off offset:64
	global_load_dwordx2 v[150:151], v[128:129], off offset:80
	global_load_dwordx2 v[148:149], v[128:129], off offset:96
	global_load_dwordx2 v[146:147], v[128:129], off offset:112
	v_add_u32_e32 v128, 0x20800, v133
	v_pk_fma_f32 v[64:65], v[142:143], v[112:113], v[64:65] op_sel_hi:[0,1,1]
	v_pk_fma_f32 v[66:67], v[142:143], v[114:115], v[66:67] op_sel_hi:[0,1,1]
	v_pk_fma_f32 v[68:69], v[142:143], v[116:117], v[68:69] op_sel_hi:[0,1,1]
	v_pk_fma_f32 v[70:71], v[142:143], v[118:119], v[70:71] op_sel_hi:[0,1,1]
	v_pk_fma_f32 v[72:73], v[142:143], v[120:121], v[72:73] op_sel_hi:[0,1,1]
	v_pk_fma_f32 v[74:75], v[142:143], v[122:123], v[74:75] op_sel_hi:[0,1,1]
	v_pk_fma_f32 v[76:77], v[142:143], v[124:125], v[76:77] op_sel_hi:[0,1,1]
	v_pk_fma_f32 v[78:79], v[142:143], v[126:127], v[78:79] op_sel_hi:[0,1,1]
	v_pk_fma_f32 v[32:33], v[142:143], v[96:97], v[32:33] op_sel_hi:[0,1,1]
	v_pk_fma_f32 v[34:35], v[142:143], v[98:99], v[34:35] op_sel_hi:[0,1,1]
	v_pk_fma_f32 v[36:37], v[142:143], v[100:101], v[36:37] op_sel_hi:[0,1,1]
	v_pk_fma_f32 v[38:39], v[142:143], v[102:103], v[38:39] op_sel_hi:[0,1,1]
	v_pk_fma_f32 v[40:41], v[142:143], v[104:105], v[40:41] op_sel_hi:[0,1,1]
	v_pk_fma_f32 v[42:43], v[142:143], v[106:107], v[42:43] op_sel_hi:[0,1,1]
	v_pk_fma_f32 v[44:45], v[142:143], v[108:109], v[44:45] op_sel_hi:[0,1,1]
	v_pk_fma_f32 v[46:47], v[142:143], v[110:111], v[46:47] op_sel_hi:[0,1,1]
	s_add_i32 s6, s6, 0x21800
	s_waitcnt vmcnt(15)
	s_waitcnt vmcnt(14)
	s_waitcnt vmcnt(13)
	s_waitcnt vmcnt(12)
	s_waitcnt vmcnt(11)
	s_waitcnt vmcnt(10)
	s_waitcnt vmcnt(9)
	s_waitcnt vmcnt(8)
	s_waitcnt vmcnt(7)
	s_waitcnt vmcnt(6)
	s_waitcnt vmcnt(5)
	s_waitcnt vmcnt(4)
	s_waitcnt vmcnt(3)
	s_waitcnt vmcnt(2)
	s_waitcnt vmcnt(1)
	s_waitcnt vmcnt(0)
	ds_read2_b32 v[162:163], v128 offset1:32
	v_lshlrev_b32_e32 v190, 16, v178
	v_and_b32_e32 v191, 0xffff0000, v178
	s_waitcnt lgkmcnt(0)
	v_div_scale_f32 v128, s[2:3], v162, v162, v189
	v_rcp_f32_e32 v129, v128
	s_lshl_b32 s2, s56, 1
	v_add3_u32 v136, v132, v136, s2
	v_fma_f32 v130, -v128, v129, 1.0
	v_fmac_f32_e32 v129, v130, v129
	v_div_scale_f32 v130, vcc, v189, v162, v189
	v_mul_f32_e32 v131, v130, v129
	v_fma_f32 v133, -v128, v131, v130
	v_fmac_f32_e32 v131, v133, v129
	v_fma_f32 v128, -v128, v131, v130
	v_div_fmas_f32 v128, v128, v129, v131
	v_div_fixup_f32 v162, v128, v162, v189
	ds_read2_b64 v[132:135], v136 offset1:2
	ds_read2_b64 v[128:131], v136 offset0:4 offset1:6
	s_waitcnt lgkmcnt(1)
	v_lshlrev_b32_e32 v112, 16, v132
	v_and_b32_e32 v113, 0xffff0000, v132
	v_mul_f32_e32 v132, 0xbfb8aa3b, v190
	v_exp_f32_e32 v132, v132
	v_lshlrev_b32_e32 v114, 16, v133
	v_and_b32_e32 v115, 0xffff0000, v133
	v_and_b32_e32 v133, 0xffff0000, v179
	v_add_f32_e32 v132, 1.0, v132
	v_rcp_f32_e32 v192, v132
	v_lshlrev_b32_e32 v132, 16, v179
	v_mul_f32_e32 v178, 0xbfb8aa3b, v132
	v_pk_fma_f32 v[66:67], v[162:163], v[114:115], v[66:67] op_sel_hi:[0,1,1]
	v_mul_f32_e32 v114, 0xbfb8aa3b, v133
	v_exp_f32_e32 v178, v178
	v_exp_f32_e32 v114, v114
	v_lshlrev_b32_e32 v116, 16, v134
	v_and_b32_e32 v117, 0xffff0000, v134
	v_add_f32_e32 v178, 1.0, v178
	v_add_f32_e32 v114, 1.0, v114
	v_rcp_f32_e32 v178, v178
	v_rcp_f32_e32 v179, v114
	v_pk_fma_f32 v[68:69], v[162:163], v[116:117], v[68:69] op_sel_hi:[0,1,1]
	v_lshlrev_b32_e32 v118, 16, v135
	v_and_b32_e32 v119, 0xffff0000, v135
	v_pk_mul_f32 v[114:115], v[178:179], v[132:133]
	v_lshlrev_b32_e32 v132, 16, v176
	v_and_b32_e32 v133, 0xffff0000, v176
	v_mul_f32_e32 v134, 0xbfb8aa3b, v132
	v_mul_f32_e32 v116, 0xbfb8aa3b, v133
	v_exp_f32_e32 v134, v134
	v_exp_f32_e32 v116, v116
	v_pk_fma_f32 v[70:71], v[162:163], v[118:119], v[70:71] op_sel_hi:[0,1,1]
	s_waitcnt lgkmcnt(0)
	v_lshlrev_b32_e32 v120, 16, v128
	v_add_f32_e32 v134, 1.0, v134
	v_add_f32_e32 v116, 1.0, v116
	v_rcp_f32_e32 v178, v134
	v_rcp_f32_e32 v179, v116
	v_and_b32_e32 v121, 0xffff0000, v128
	v_pk_fma_f32 v[72:73], v[162:163], v[120:121], v[72:73] op_sel_hi:[0,1,1]
	v_lshlrev_b32_e32 v122, 16, v129
	v_pk_mul_f32 v[116:117], v[178:179], v[132:133]
	v_lshlrev_b32_e32 v132, 16, v177
	v_and_b32_e32 v133, 0xffff0000, v177
	v_mul_f32_e32 v134, 0xbfb8aa3b, v132
	v_mul_f32_e32 v118, 0xbfb8aa3b, v133
	v_exp_f32_e32 v134, v134
	v_exp_f32_e32 v118, v118
	v_and_b32_e32 v123, 0xffff0000, v129
	v_and_b32_e32 v129, 0xffff0000, v175
	v_add_f32_e32 v134, 1.0, v134
	v_add_f32_e32 v118, 1.0, v118
	v_rcp_f32_e32 v134, v134
	v_rcp_f32_e32 v135, v118
	v_pk_fma_f32 v[74:75], v[162:163], v[122:123], v[74:75] op_sel_hi:[0,1,1]
	v_mul_f32_e32 v122, 0xbfb8aa3b, v129
	v_exp_f32_e32 v122, v122
	v_pk_mul_f32 v[118:119], v[134:135], v[132:133]
	v_lshlrev_b32_e32 v132, 16, v174
	v_and_b32_e32 v133, 0xffff0000, v174
	v_mul_f32_e32 v128, 0xbfb8aa3b, v132
	v_mul_f32_e32 v120, 0xbfb8aa3b, v133
	v_exp_f32_e32 v128, v128
	v_exp_f32_e32 v120, v120
	v_add_f32_e32 v122, 1.0, v122
	v_lshlrev_b32_e32 v124, 16, v130
	v_add_f32_e32 v128, 1.0, v128
	v_add_f32_e32 v120, 1.0, v120
	v_rcp_f32_e32 v134, v128
	v_rcp_f32_e32 v135, v120
	v_lshlrev_b32_e32 v128, 16, v175
	v_and_b32_e32 v125, 0xffff0000, v130
	v_pk_fma_f32 v[76:77], v[162:163], v[124:125], v[76:77] op_sel_hi:[0,1,1]
	v_pk_mul_f32 v[120:121], v[134:135], v[132:133]
	v_mul_f32_e32 v132, 0xbfb8aa3b, v128
	v_exp_f32_e32 v132, v132
	v_rcp_f32_e32 v133, v122
	v_lshlrev_b32_e32 v126, 16, v131
	v_and_b32_e32 v127, 0xffff0000, v131
	v_add_f32_e32 v132, 1.0, v132
	v_rcp_f32_e32 v132, v132
	v_pk_fma_f32 v[78:79], v[162:163], v[126:127], v[78:79] op_sel_hi:[0,1,1]
	v_pk_fma_f32 v[64:65], v[162:163], v[112:113], v[64:65] op_sel_hi:[0,1,1]
	v_mul_f32_e32 v112, 0xbfb8aa3b, v191
	v_pk_mul_f32 v[122:123], v[132:133], v[128:129]
	v_lshlrev_b32_e32 v128, 16, v172
	v_and_b32_e32 v129, 0xffff0000, v172
	v_mul_f32_e32 v130, 0xbfb8aa3b, v128
	v_mul_f32_e32 v124, 0xbfb8aa3b, v129
	v_exp_f32_e32 v130, v130
	v_exp_f32_e32 v124, v124
	v_exp_f32_e32 v112, v112
	v_pk_mul_f32 v[66:67], v[114:115], v[66:67]
	v_add_f32_e32 v130, 1.0, v130
	v_add_f32_e32 v124, 1.0, v124
	v_rcp_f32_e32 v132, v130
	v_rcp_f32_e32 v133, v124
	v_add_f32_e32 v112, 1.0, v112
	v_rcp_f32_e32 v193, v112
	v_pk_mul_f32 v[114:115], v[66:67], v[66:67]
	v_pk_mul_f32 v[124:125], v[132:133], v[128:129]
	v_lshlrev_b32_e32 v128, 16, v173
	v_and_b32_e32 v129, 0xffff0000, v173
	v_mul_f32_e32 v130, 0xbfb8aa3b, v128
	v_mul_f32_e32 v126, 0xbfb8aa3b, v129
	v_exp_f32_e32 v130, v130
	v_exp_f32_e32 v126, v126
	v_lshlrev_b32_e32 v132, 16, v170
	v_and_b32_e32 v133, 0xffff0000, v170
	v_add_f32_e32 v130, 1.0, v130
	v_add_f32_e32 v126, 1.0, v126
	v_rcp_f32_e32 v130, v130
	v_rcp_f32_e32 v131, v126
	v_pk_mul_f32 v[112:113], v[192:193], v[190:191]
	v_pk_mul_f32 v[68:69], v[116:117], v[68:69]
	v_pk_mul_f32 v[64:65], v[112:113], v[64:65]
	v_pk_mul_f32 v[126:127], v[130:131], v[128:129]
	ds_read2_b64 v[128:131], v136 offset0:8 offset1:10
	v_pk_mul_f32 v[112:113], v[64:65], v[64:65]
	v_pk_mul_f32 v[116:117], v[68:69], v[68:69]
	v_add_f32_e32 v112, v112, v113
	v_add_f32_e32 v112, v114, v112
	s_waitcnt lgkmcnt(0)
	v_lshlrev_b32_e32 v96, 16, v128
	v_and_b32_e32 v97, 0xffff0000, v128
	v_mul_f32_e32 v128, 0xbfb8aa3b, v132
	v_pk_fma_f32 v[32:33], v[162:163], v[96:97], v[32:33] op_sel_hi:[0,1,1]
	v_mul_f32_e32 v96, 0xbfb8aa3b, v133
	v_exp_f32_e32 v128, v128
	v_exp_f32_e32 v96, v96
	v_lshlrev_b32_e32 v98, 16, v129
	v_and_b32_e32 v99, 0xffff0000, v129
	v_add_f32_e32 v128, 1.0, v128
	v_add_f32_e32 v96, 1.0, v96
	v_rcp_f32_e32 v134, v128
	v_rcp_f32_e32 v135, v96
	v_lshlrev_b32_e32 v128, 16, v171
	v_and_b32_e32 v129, 0xffff0000, v171
	v_pk_fma_f32 v[34:35], v[162:163], v[98:99], v[34:35] op_sel_hi:[0,1,1]
	v_pk_mul_f32 v[96:97], v[134:135], v[132:133]
	v_mul_f32_e32 v132, 0xbfb8aa3b, v128
	v_mul_f32_e32 v98, 0xbfb8aa3b, v129
	v_exp_f32_e32 v132, v132
	v_exp_f32_e32 v98, v98
	v_lshlrev_b32_e32 v100, 16, v130
	v_and_b32_e32 v101, 0xffff0000, v130
	v_add_f32_e32 v132, 1.0, v132
	v_add_f32_e32 v98, 1.0, v98
	v_rcp_f32_e32 v132, v132
	v_rcp_f32_e32 v133, v98
	v_pk_fma_f32 v[36:37], v[162:163], v[100:101], v[36:37] op_sel_hi:[0,1,1]
	v_lshlrev_b32_e32 v102, 16, v131
	v_and_b32_e32 v103, 0xffff0000, v131
	v_pk_mul_f32 v[98:99], v[132:133], v[128:129]
	v_lshlrev_b32_e32 v128, 16, v168
	v_and_b32_e32 v129, 0xffff0000, v168
	v_mul_f32_e32 v130, 0xbfb8aa3b, v128
	v_mul_f32_e32 v100, 0xbfb8aa3b, v129
	v_exp_f32_e32 v130, v130
	v_exp_f32_e32 v100, v100
	v_pk_fma_f32 v[38:39], v[162:163], v[102:103], v[38:39] op_sel_hi:[0,1,1]
	v_add_f32_e32 v112, v115, v112
	v_add_f32_e32 v130, 1.0, v130
	v_add_f32_e32 v100, 1.0, v100
	v_rcp_f32_e32 v132, v130
	v_rcp_f32_e32 v133, v100
	v_pk_mul_f32 v[70:71], v[118:119], v[70:71]
	v_add_f32_e32 v112, v116, v112
	v_pk_mul_f32 v[118:119], v[70:71], v[70:71]
	v_pk_mul_f32 v[100:101], v[132:133], v[128:129]
	v_lshlrev_b32_e32 v128, 16, v169
	v_and_b32_e32 v129, 0xffff0000, v169
	v_mul_f32_e32 v130, 0xbfb8aa3b, v128
	v_mul_f32_e32 v102, 0xbfb8aa3b, v129
	v_exp_f32_e32 v130, v130
	v_exp_f32_e32 v102, v102
	v_lshlrev_b32_e32 v132, 16, v166
	v_and_b32_e32 v133, 0xffff0000, v166
	v_add_f32_e32 v130, 1.0, v130
	v_add_f32_e32 v102, 1.0, v102
	v_rcp_f32_e32 v130, v130
	v_rcp_f32_e32 v131, v102
	v_add_f32_e32 v112, v117, v112
	v_pk_mul_f32 v[72:73], v[120:121], v[72:73]
	v_add_f32_e32 v112, v118, v112
	v_pk_mul_f32 v[102:103], v[130:131], v[128:129]
	ds_read2_b64 v[128:131], v136 offset0:12 offset1:14
	v_pk_mul_f32 v[120:121], v[72:73], v[72:73]
	v_add_f32_e32 v112, v119, v112
	v_pk_mul_f32 v[74:75], v[122:123], v[74:75]
	v_add_f32_e32 v112, v120, v112
	s_waitcnt lgkmcnt(0)
	v_lshlrev_b32_e32 v104, 16, v128
	v_and_b32_e32 v105, 0xffff0000, v128
	v_mul_f32_e32 v128, 0xbfb8aa3b, v132
	v_pk_fma_f32 v[40:41], v[162:163], v[104:105], v[40:41] op_sel_hi:[0,1,1]
	v_mul_f32_e32 v104, 0xbfb8aa3b, v133
	v_exp_f32_e32 v128, v128
	v_exp_f32_e32 v104, v104
	v_lshlrev_b32_e32 v106, 16, v129
	v_and_b32_e32 v107, 0xffff0000, v129
	v_add_f32_e32 v128, 1.0, v128
	v_add_f32_e32 v104, 1.0, v104
	v_rcp_f32_e32 v134, v128
	v_rcp_f32_e32 v135, v104
	v_lshlrev_b32_e32 v128, 16, v167
	v_and_b32_e32 v129, 0xffff0000, v167
	v_pk_fma_f32 v[42:43], v[162:163], v[106:107], v[42:43] op_sel_hi:[0,1,1]
	v_pk_mul_f32 v[104:105], v[134:135], v[132:133]
	v_mul_f32_e32 v132, 0xbfb8aa3b, v128
	v_mul_f32_e32 v106, 0xbfb8aa3b, v129
	v_exp_f32_e32 v132, v132
	v_exp_f32_e32 v106, v106
	v_lshlrev_b32_e32 v108, 16, v130
	v_and_b32_e32 v109, 0xffff0000, v130
	v_add_f32_e32 v132, 1.0, v132
	v_add_f32_e32 v106, 1.0, v106
	v_rcp_f32_e32 v132, v132
	v_rcp_f32_e32 v133, v106
	v_pk_fma_f32 v[44:45], v[162:163], v[108:109], v[44:45] op_sel_hi:[0,1,1]
	v_pk_mul_f32 v[122:123], v[74:75], v[74:75]
	v_add_f32_e32 v112, v121, v112
	v_pk_mul_f32 v[106:107], v[132:133], v[128:129]
	v_lshlrev_b32_e32 v128, 16, v164
	v_and_b32_e32 v129, 0xffff0000, v164
	v_mul_f32_e32 v130, 0xbfb8aa3b, v128
	v_mul_f32_e32 v108, 0xbfb8aa3b, v129
	v_exp_f32_e32 v130, v130
	v_exp_f32_e32 v108, v108
	v_pk_mul_f32 v[76:77], v[124:125], v[76:77]
	v_add_f32_e32 v112, v122, v112
	v_pk_mul_f32 v[124:125], v[76:77], v[76:77]
	v_add_f32_e32 v130, 1.0, v130
	v_add_f32_e32 v108, 1.0, v108
	v_add_f32_e32 v112, v123, v112
	v_pk_mul_f32 v[78:79], v[126:127], v[78:79]
	v_rcp_f32_e32 v132, v130
	v_rcp_f32_e32 v133, v108
	v_add_f32_e32 v112, v124, v112
	v_pk_mul_f32 v[126:127], v[78:79], v[78:79]
	v_add_f32_e32 v112, v125, v112
	v_pk_mul_f32 v[96:97], v[96:97], v[32:33]
	v_add_f32_e32 v112, v126, v112
	v_pk_mul_f32 v[32:33], v[96:97], v[96:97]
	v_add_f32_e32 v112, v127, v112
	v_pk_mul_f32 v[98:99], v[98:99], v[34:35]
	v_pk_mul_f32 v[108:109], v[132:133], v[128:129]
	v_lshlrev_b32_e32 v110, 16, v131
	v_and_b32_e32 v111, 0xffff0000, v131
	v_lshlrev_b32_e32 v128, 16, v165
	v_and_b32_e32 v129, 0xffff0000, v165
	v_add_f32_e32 v32, v32, v112
	v_pk_mul_f32 v[34:35], v[98:99], v[98:99]
	v_mul_f32_e32 v130, 0xbfb8aa3b, v128
	v_pk_fma_f32 v[46:47], v[162:163], v[110:111], v[46:47] op_sel_hi:[0,1,1]
	v_mul_f32_e32 v110, 0xbfb8aa3b, v129
	v_add_f32_e32 v32, v33, v32
	v_pk_mul_f32 v[100:101], v[100:101], v[36:37]
	v_exp_f32_e32 v130, v130
	v_exp_f32_e32 v110, v110
	v_add_f32_e32 v32, v34, v32
	v_pk_mul_f32 v[36:37], v[100:101], v[100:101]
	v_add_f32_e32 v32, v35, v32
	v_pk_mul_f32 v[102:103], v[102:103], v[38:39]
	v_add_f32_e32 v32, v36, v32
	v_pk_mul_f32 v[38:39], v[102:103], v[102:103]
	v_add_f32_e32 v32, v37, v32
	v_pk_mul_f32 v[104:105], v[104:105], v[40:41]
	v_add_f32_e32 v130, 1.0, v130
	v_add_f32_e32 v110, 1.0, v110
	v_add_f32_e32 v32, v38, v32
	v_pk_mul_f32 v[40:41], v[104:105], v[104:105]
	v_rcp_f32_e32 v130, v130
	v_rcp_f32_e32 v131, v110
	v_add_f32_e32 v32, v39, v32
	v_pk_mul_f32 v[106:107], v[106:107], v[42:43]
	v_add_f32_e32 v32, v40, v32
	v_pk_mul_f32 v[42:43], v[106:107], v[106:107]
	v_add_f32_e32 v32, v41, v32
	v_pk_mul_f32 v[108:109], v[108:109], v[44:45]
	v_add_f32_e32 v32, v42, v32
	v_pk_mul_f32 v[44:45], v[108:109], v[108:109]
	v_pk_mul_f32 v[110:111], v[130:131], v[128:129]
	v_add_f32_e32 v32, v43, v32
	v_pk_mul_f32 v[110:111], v[110:111], v[46:47]
	v_add_f32_e32 v32, v44, v32
	v_pk_mul_f32 v[46:47], v[110:111], v[110:111]
	v_add_f32_e32 v32, v45, v32
	v_add_f32_e32 v32, v46, v32
	v_xor_b32_e32 v113, 32, v184
	v_add_u32_e32 v114, 64, v139
	v_add_f32_e32 v112, v47, v32
	v_add_u32_e32 v32, 0x10400, v136
	v_cmp_lt_i32_e32 vcc, v113, v114
	ds_read2_b64 v[44:47], v32 offset1:2
	ds_read2_b64 v[40:43], v32 offset0:4 offset1:6
	ds_read2_b64 v[36:39], v32 offset0:8 offset1:10
	ds_read2_b64 v[32:35], v32 offset0:12 offset1:14
	v_cndmask_b32_e32 v113, v184, v113, vcc
	v_lshlrev_b32_e32 v115, 2, v113
	ds_bpermute_b32 v114, v115, v112
	v_add_u32_e32 v113, s6, v188
	s_and_saveexec_b64 s[2:3], s[42:43]
	s_cbranch_execz .LBB0_1847
	s_waitcnt lgkmcnt(0)
	v_add_f32_e32 v112, v112, v114
	ds_write_b32 v113, v112
